# attention item prologue: full vmcnt(0) drain removed, K/V tile writes and Q fragments each wait at their own counted first-consumer waits
# speedup vs baseline: 1.0081x; 1.0018x over previous
.Latt_noprio:
	s_and_b32 s0, s3, 4
	s_lshl_b32 s1, s23, 1
	s_and_b32 s1, s1, 0x200
	s_lshl_b32 s0, s0, 6
	s_or_b32 s43, s1, s0
	s_lshr_b32 s1, s23, 5
	s_ashr_i32 s0, s23, 9
	s_and_b32 s1, s1, 8
	s_and_b32 s4, s23, 7
	s_lshl_b32 s6, s23, 5
	s_or_b32 s4, s1, s4
	s_lshl_b32 s1, s0, 13
	s_and_b32 s6, s6, 0x1f00
	s_or_b32 s6, s1, s6
	s_ashr_i32 s7, s6, 31
	s_ashr_i32 s1, s0, 31
	s_lshl_b64 s[6:7], s[6:7], 12
	s_add_u32 s6, s48, s6
	s_addc_u32 s7, s49, s7
	s_lshl_b32 s8, s4, 8
	s_add_u32 s38, s6, s8
	s_addc_u32 s39, s7, 0
	s_lshl_b32 s4, s4, 6
	s_and_b32 s4, s4, 0x300
	s_lshl_b64 s[0:1], s[0:1], 23
	v_mov_b32_e32 v74, v188
	s_or_b32 s4, s0, s4
	s_add_u32 s28, s50, s4
	v_ashrrev_i32_e32 v16, 4, v74
	v_lshlrev_b32_e32 v22, 3, v74
	v_add_u32_e32 v18, 32, v16
	s_addc_u32 s29, s51, s1
	v_and_b32_e32 v0, 0x78, v22
	v_ashrrev_i32_e32 v17, 31, v16
	v_ashrrev_i32_e32 v19, 31, v18
	s_add_u32 s26, s67, s4
	v_lshlrev_b32_e32 v23, 1, v0
	v_lshlrev_b64 v[48:49], 10, v[16:17]
	v_lshlrev_b64 v[12:13], 10, v[18:19]
	s_addc_u32 s27, s72, s1
	v_or_b32_e32 v50, v48, v23
	v_mov_b32_e32 v51, v49
	v_or_b32_e32 v12, v12, v23
	v_lshl_add_u64 v[0:1], s[26:27], 0, v[50:51]
	v_lshl_add_u64 v[4:5], s[26:27], 0, v[12:13]
	global_load_dwordx4 v[0:3], v[0:1], off
	s_nop 0
	global_load_dwordx4 v[4:7], v[4:5], off
	v_lshl_add_u64 v[8:9], s[28:29], 0, v[50:51]
	global_load_dwordx4 v[8:11], v[8:9], off
	v_readfirstlane_b32 s4, v74
	s_ashr_i32 s6, s4, 1
	v_lshl_add_u64 v[12:13], s[28:29], 0, v[12:13]
	v_mov_b32_e32 v17, s6
	s_movk_i32 s7, 0xffe0
	global_load_dwordx4 v[12:15], v[12:13], off
	v_bfi_b32 v20, s7, v17, v74
	v_ashrrev_i32_e32 v21, 31, v20
	v_bfe_u32 v198, v74, 5, 1
	v_lshlrev_b64 v[20:21], 12, v[20:21]
	v_lshl_add_u64 v[20:21], s[38:39], 0, v[20:21]
	v_lshlrev_b32_e32 v96, 4, v198
	v_lshl_add_u64 v[20:21], v[20:21], 0, v[96:97]
	global_load_dwordx4 v[122:125], v[20:21], off
	global_load_dwordx4 v[114:117], v[20:21], off offset:32
	global_load_dwordx4 v[126:129], v[20:21], off offset:64
	global_load_dwordx4 v[118:121], v[20:21], off offset:96
	global_load_dwordx4 v[110:113], v[20:21], off offset:128
	global_load_dwordx4 v[106:109], v[20:21], off offset:160
	global_load_dwordx4 v[102:105], v[20:21], off offset:192
	global_load_dwordx4 v[98:101], v[20:21], off offset:224
	v_and_b32_e32 v17, 0xfffff0, v16
	v_lshlrev_b32_e32 v19, 1, v16
	v_lshrrev_b32_e32 v24, 1, v16
	v_and_b32_e32 v25, 3, v16
	v_and_or_b32 v17, v19, 8, v17
	v_and_or_b32 v19, v24, 4, v25
	v_and_b32_e32 v24, 0xfffff0, v18
	v_lshlrev_b32_e32 v25, 1, v18
	v_bfe_u32 v22, v22, 5, 2
	v_lshrrev_b32_e32 v17, 1, v17
	v_and_or_b32 v24, v25, 8, v24
	v_or_b32_e32 v17, v17, v22
	v_lshrrev_b32_e32 v24, 1, v24
	v_lshlrev_b32_e32 v19, 6, v19
	v_and_b32_e32 v26, 48, v23
	v_lshlrev_b32_e32 v17, 9, v17
	v_or_b32_e32 v22, v24, v22
	v_or3_b32 v17, v17, v19, v26
	v_lshlrev_b32_e32 v22, 9, v22
	v_or3_b32 v19, v22, v19, v26
	v_add_u32_e32 v204, 0, v17
	v_add_u32_e32 v205, 0, v19
	v_and_b32_e32 v199, 31, v74
	v_lshlrev_b32_e32 v52, 4, v74
	v_and_b32_e32 v75, 63, v74
	s_and_b32 s4, s4, 0x3fffffc0
	s_lshl_b32 s4, s4, 2
	s_add_i32 s41, s4, 0
	s_mov_b32 s4, s5
	s_and_b32 s40, s6, 0xffffffe0
	s_mov_b32 s6, s5
	s_mov_b32 s7, s5
	s_mov_b32 s8, s5
	s_waitcnt vmcnt(11)
	ds_write_b128 v204, v[0:3]
	s_waitcnt vmcnt(10)
	ds_write_b128 v205, v[4:7]
	v_lshlrev_b32_e32 v0, 8, v16
	v_and_b32_e32 v1, 0x70, v74
	v_bitop3_b32 v0, v23, v0, v1 bitop3:0xde
	v_add_u32_e32 v206, 0, v0
	v_lshlrev_b32_e32 v0, 8, v18
	s_waitcnt vmcnt(9)
	ds_write_b128 v206, v[8:11] offset:32768
	v_bitop3_b32 v0, v23, v0, v1 bitop3:0xde
	v_lshlrev_b32_e32 v8, 8, v199
	v_and_b32_e32 v9, 0x70, v52
	v_add_u32_e32 v207, 0, v0
	v_bitop3_b32 v0, v96, v8, v9 bitop3:0xde
	v_add_u32_e32 v208, 0, v0
	s_waitcnt vmcnt(8)
	ds_write_b128 v207, v[12:15] offset:32768
	s_waitcnt lgkmcnt(0)
	s_barrier
	ds_read_b128 v[0:3], v208 offset:32768
	ds_read_b128 v[4:7], v208 offset:40960
	s_waitcnt vmcnt(7) lgkmcnt(1)
	v_mfma_f32_32x32x16_bf16 v[32:47], v[0:3], v[122:125], 0
	v_or_b32_e32 v0, 32, v96
	v_bitop3_b32 v0, v0, v8, v9 bitop3:0xde
	v_add_u32_e32 v215, 0, v0
	v_lshlrev_b32_e32 v10, 3, v75
	v_lshlrev_b32_e32 v12, 1, v74
	s_mov_b32 s9, s5
	s_mov_b32 s10, s5
	s_waitcnt lgkmcnt(0)
	v_mfma_f32_32x32x16_bf16 v[16:31], v[4:7], v[122:125], 0
	ds_read_b128 v[0:3], v215 offset:32768
	ds_read_b128 v[4:7], v215 offset:40960
	s_mov_b32 s11, s5
	s_mov_b32 s12, s5
	s_mov_b32 s13, s5
	s_mov_b32 s14, s5
	s_mov_b32 s15, s5
	s_mov_b32 s16, s5
	s_waitcnt vmcnt(6) lgkmcnt(1)
	v_mfma_f32_32x32x16_bf16 v[32:47], v[0:3], v[114:117], v[32:47]
	v_or_b32_e32 v0, 64, v96
	v_bitop3_b32 v0, v0, v8, v9 bitop3:0xde
	v_add_u32_e32 v214, 0, v0
	s_mov_b32 s17, s5
	s_mov_b32 s18, s5
	s_mov_b32 s19, s5
	s_add_i32 s41, s41, 0x10000
	s_waitcnt lgkmcnt(0)
	v_mfma_f32_32x32x16_bf16 v[16:31], v[4:7], v[114:117], v[16:31]
	ds_read_b128 v[0:3], v214 offset:32768
	ds_read_b128 v[4:7], v214 offset:40960
	s_cmp_lg_u32 0, -1
	s_cselect_b32 s44, 0, 0
	s_mov_b32 s42, 1
	v_cmp_gt_u32_e64 s[36:37], 32, v75
	v_lshl_add_u32 v200, v199, 2, s41
	v_mov_b32_e32 v201, 0
	s_waitcnt vmcnt(5) lgkmcnt(1)
	v_mfma_f32_32x32x16_bf16 v[32:47], v[0:3], v[126:129], v[32:47]
	v_or_b32_e32 v0, 0x60, v96
	v_bitop3_b32 v0, v0, v8, v9 bitop3:0xde
	v_add_u32_e32 v211, 0, v0
	s_waitcnt lgkmcnt(0)
	v_mfma_f32_32x32x16_bf16 v[16:31], v[4:7], v[126:129], v[16:31]
	ds_read_b128 v[0:3], v211 offset:32768
	ds_read_b128 v[4:7], v211 offset:40960
	s_waitcnt vmcnt(4) lgkmcnt(1)
	v_mfma_f32_32x32x16_bf16 v[32:47], v[0:3], v[118:121], v[32:47]
	v_or_b32_e32 v0, 0x80, v96
	v_bitop3_b32 v0, v0, v8, v9 bitop3:0xde
	v_add_u32_e32 v210, 0, v0
	s_waitcnt lgkmcnt(0)
	v_mfma_f32_32x32x16_bf16 v[16:31], v[4:7], v[118:121], v[16:31]
	ds_read_b128 v[0:3], v210 offset:32768
	ds_read_b128 v[4:7], v210 offset:40960
	s_waitcnt vmcnt(3) lgkmcnt(1)
	v_mfma_f32_32x32x16_bf16 v[32:47], v[0:3], v[110:113], v[32:47]
	v_or_b32_e32 v0, 0xa0, v96
	v_bitop3_b32 v0, v0, v8, v9 bitop3:0xde
	v_add_u32_e32 v209, 0, v0
	ds_read_b128 v[0:3], v209 offset:32768
	s_waitcnt lgkmcnt(1)
	v_mfma_f32_32x32x16_bf16 v[16:31], v[4:7], v[110:113], v[16:31]
	ds_read_b128 v[4:7], v209 offset:40960
	s_waitcnt vmcnt(2) lgkmcnt(1)
	v_mfma_f32_32x32x16_bf16 v[32:47], v[0:3], v[106:109], v[32:47]
	v_and_b32_e32 v0, 0xc0, v52
	v_and_or_b32 v11, v10, 24, v0
	v_or_b32_e32 v0, 0xc0, v96
	v_bitop3_b32 v0, v0, v8, v9 bitop3:0xde
	v_add_u32_e32 v212, 0, v0
	ds_read_b128 v[0:3], v212 offset:32768
	s_waitcnt lgkmcnt(1)
	v_mfma_f32_32x32x16_bf16 v[16:31], v[4:7], v[106:109], v[16:31]
	v_and_b32_e32 v4, 32, v12
	v_and_b32_e32 v5, 0x100, v10
	v_or3_b32 v76, v11, v4, v5
	ds_read_b128 v[4:7], v212 offset:40960
	v_add_u32_e32 v203, s44, v76
	s_waitcnt vmcnt(1) lgkmcnt(1)
	v_mfma_f32_32x32x16_bf16 v[32:47], v[0:3], v[102:105], v[32:47]
	v_or_b32_e32 v0, 0xe0, v96
	v_bitop3_b32 v0, v0, v8, v9 bitop3:0xde
	v_add_u32_e32 v213, 0, v0
	ds_read_b128 v[0:3], v213 offset:32768
	ds_read_b128 v[52:55], v213 offset:40960
	s_waitcnt lgkmcnt(2)
	v_mfma_f32_32x32x16_bf16 v[16:31], v[4:7], v[102:105], v[16:31]
	s_waitcnt vmcnt(0) lgkmcnt(1)
	v_mfma_f32_32x32x16_bf16 v[32:47], v[0:3], v[98:101], v[32:47]
	v_mov_b64_e32 v[0:1], s[4:5]
	v_mov_b64_e32 v[2:3], s[6:7]
	v_mov_b64_e32 v[4:5], s[8:9]
	v_mov_b64_e32 v[6:7], s[10:11]
	v_mov_b64_e32 v[8:9], s[12:13]
	v_mov_b64_e32 v[10:11], s[14:15]
	v_mov_b64_e32 v[12:13], s[16:17]
	s_waitcnt lgkmcnt(0)
	v_mfma_f32_32x32x16_bf16 v[16:31], v[52:55], v[98:101], v[16:31]
	s_nop 2
	v_max_f32_e32 v52, v33, v33
	v_max_f32_e32 v53, v32, v32
	v_max_f32_e32 v52, v53, v52
	v_max3_f32 v52, v52, v34, v35
	v_max3_f32 v52, v52, v36, v37
	v_max3_f32 v52, v52, v38, v39
	v_max3_f32 v52, v52, v40, v41
	v_max3_f32 v52, v52, v42, v43
	v_max3_f32 v52, v52, v44, v45
	v_max3_f32 v52, v52, v46, v47
	v_max3_f32 v68, v52, v16, v17
	v_max3_f32 v68, v68, v18, v19
	v_max3_f32 v68, v68, v20, v21
	v_max3_f32 v68, v68, v22, v23
	v_mov_b64_e32 v[14:15], s[18:19]
	s_mov_b64 s[6:7], 0x10000
	v_max3_f32 v68, v68, v24, v25
	v_lshl_add_u64 v[60:61], v[50:51], 0, s[6:7]
	s_mov_b64 s[6:7], 0x18000
	v_max3_f32 v68, v68, v26, v27
	v_lshl_add_u64 v[62:63], v[50:51], 0, s[6:7]
	v_max3_f32 v68, v68, v28, v29
	s_mov_b64 s[6:7], 0x28000
	v_lshl_add_u64 v[52:53], s[26:27], 0, v[60:61]
	v_lshl_add_u64 v[56:57], s[26:27], 0, v[62:63]
	v_lshl_add_u64 v[60:61], s[28:29], 0, v[60:61]
	v_lshl_add_u64 v[64:65], s[28:29], 0, v[62:63]
	v_max3_f32 v77, v68, v30, v31
	v_lshl_add_u64 v[68:69], v[50:51], 0, s[6:7]
	global_load_dwordx4 v[52:55], v[52:53], off
	s_nop 0
	global_load_dwordx4 v[56:59], v[56:57], off
	s_nop 0
	global_load_dwordx4 v[60:63], v[60:61], off
	s_nop 0
	global_load_dwordx4 v[64:67], v[64:65], off
	v_lshl_add_u64 v[70:71], s[28:29], 0, v[68:69]
	v_lshl_add_u64 v[50:51], v[50:51], 0, s[30:31]
	v_lshl_add_u64 v[68:69], s[26:27], 0, v[68:69]
	v_lshl_add_u64 v[72:73], s[28:29], 0, v[50:51]
	global_load_dwordx4 v[138:141], v[70:71], off
	global_load_dwordx4 v[130:133], v[72:73], off
	v_lshl_add_u64 v[50:51], s[26:27], 0, v[50:51]
	global_load_dwordx4 v[142:145], v[68:69], off
	global_load_dwordx4 v[134:137], v[50:51], off
	v_mov_b32_e32 v50, v77
	s_nop 1
	v_permlane32_swap_b32_e32 v77, v50
	v_max_f32_e32 v50, v50, v50
	v_max_f32_e32 v51, v77, v77
	v_max_f32_e32 v50, v51, v50
	v_add_f32_e32 v51, 0x7149f2ca, v50
	v_max_f32_e32 v50, 0xf149f2ca, v50
	v_cmp_ge_f32_e32 vcc, s97, v51
	v_sub_f32_e32 v51, 0xf149f2ca, v50
	v_mul_f32_e32 v51, 0x3e0293ee, v51
	v_exp_f32_e32 v51, v51
	s_cmp_eq_u64 vcc, exec
	s_cselect_b64 vcc, -1, 0
	v_cndmask_b32_e32 v170, v50, v197, vcc
	v_mul_f32_e32 v50, 0xbe0293ee, v170
	v_cndmask_b32_e64 v216, v51, 1.0, vcc
	v_mov_b32_e32 v51, v50
	v_fmac_f32_e32 v51, 0x3e0293ee, v47
	v_pk_fma_f32 v[156:157], v[18:19], s[22:23], v[50:51] op_sel_hi:[1,0,0]
	v_and_b32_e32 v18, 15, v74
	v_pk_fma_f32 v[158:159], v[16:17], s[22:23], v[50:51] op_sel_hi:[1,0,0]
	s_waitcnt vmcnt(4)
	v_lshl_add_u64 v[16:17], s[0:1], 0, v[48:49]
	v_lshlrev_b32_e32 v18, 4, v18
	v_readlane_b32 s0, v247, 61
	v_fmamk_f32 v32, v32, 0x3e0293ee, v50
	v_fmamk_f32 v33, v33, 0x3e0293ee, v50
	v_fmamk_f32 v34, v34, 0x3e0293ee, v50
	v_fmamk_f32 v35, v35, 0x3e0293ee, v50
	v_fmamk_f32 v36, v36, 0x3e0293ee, v50
	v_fmamk_f32 v37, v37, 0x3e0293ee, v50
	v_fmamk_f32 v38, v38, 0x3e0293ee, v50
	v_fmamk_f32 v39, v39, 0x3e0293ee, v50
	v_fmamk_f32 v40, v40, 0x3e0293ee, v50
	v_fmamk_f32 v41, v41, 0x3e0293ee, v50
	v_fmamk_f32 v42, v42, 0x3e0293ee, v50
	v_fmamk_f32 v43, v43, 0x3e0293ee, v50
	v_fmamk_f32 v44, v44, 0x3e0293ee, v50
	v_fmamk_f32 v45, v45, 0x3e0293ee, v50
	v_fmamk_f32 v46, v46, 0x3e0293ee, v50
	v_or3_b32 v16, v16, s43, v18
	v_readlane_b32 s1, v247, 62
	v_pk_fma_f32 v[152:153], v[30:31], s[22:23], v[50:51] op_sel_hi:[1,0,0]
	v_pk_fma_f32 v[154:155], v[28:29], s[22:23], v[50:51] op_sel_hi:[1,0,0]
	v_pk_fma_f32 v[160:161], v[26:27], s[22:23], v[50:51] op_sel_hi:[1,0,0]
	v_pk_fma_f32 v[146:147], v[24:25], s[22:23], v[50:51] op_sel_hi:[1,0,0]
	v_pk_fma_f32 v[148:149], v[22:23], s[22:23], v[50:51] op_sel_hi:[1,0,0]
	v_pk_fma_f32 v[150:151], v[20:21], s[22:23], v[50:51] op_sel_hi:[1,0,0]
	v_exp_f32_e32 v177, v32
	v_exp_f32_e32 v223, v33
	v_exp_f32_e32 v163, v34
	v_exp_f32_e32 v220, v35
	v_exp_f32_e32 v164, v36
	v_exp_f32_e32 v176, v37
	v_exp_f32_e32 v165, v38
	v_exp_f32_e32 v175, v39
	v_exp_f32_e32 v166, v40
	v_exp_f32_e32 v174, v41
	v_exp_f32_e32 v167, v42
	v_exp_f32_e32 v173, v43
	v_exp_f32_e32 v168, v44
	v_exp_f32_e32 v172, v45
	v_exp_f32_e32 v169, v46
	v_exp_f32_e32 v171, v51
	s_waitcnt vmcnt(7)
	ds_write_b128 v204, v[52:55] offset:16384
	s_waitcnt vmcnt(6)
	ds_write_b128 v205, v[56:59] offset:16384
	s_waitcnt vmcnt(5)
	ds_write_b128 v206, v[60:63] offset:49152
	s_waitcnt vmcnt(4)
	ds_write_b128 v207, v[64:67] offset:49152
	s_addk_i32 s44, 0x4000
	v_lshl_add_u64 v[186:187], s[0:1], 0, v[16:17]
	v_mov_b64_e32 v[62:63], v[14:15]
	v_mov_b64_e32 v[46:47], v[14:15]
	v_mov_b64_e32 v[30:31], v[14:15]
	s_waitcnt lgkmcnt(0)
	s_barrier
	v_add_u32_e32 v202, s44, v76
	v_mov_b64_e32 v[60:61], v[12:13]
	v_mov_b64_e32 v[58:59], v[10:11]
	v_mov_b64_e32 v[56:57], v[8:9]
	v_mov_b64_e32 v[54:55], v[6:7]
	v_mov_b64_e32 v[52:53], v[4:5]
	v_mov_b64_e32 v[50:51], v[2:3]
	v_mov_b64_e32 v[48:49], v[0:1]
	v_mov_b64_e32 v[44:45], v[12:13]
	v_mov_b64_e32 v[42:43], v[10:11]
	v_mov_b64_e32 v[40:41], v[8:9]
	v_mov_b64_e32 v[38:39], v[6:7]
	v_mov_b64_e32 v[36:37], v[4:5]
	v_mov_b64_e32 v[34:35], v[2:3]
	v_mov_b64_e32 v[32:33], v[0:1]
	v_mov_b64_e32 v[28:29], v[12:13]
	v_mov_b64_e32 v[26:27], v[10:11]
	v_mov_b64_e32 v[24:25], v[8:9]
	v_mov_b64_e32 v[22:23], v[6:7]
	v_mov_b64_e32 v[20:21], v[4:5]
	v_mov_b64_e32 v[18:19], v[2:3]
	v_mov_b64_e32 v[16:17], v[0:1]
